# attention fast steps: compiler-packed v_pk_add_f32 inside the MFMA stream split into scalar v_add_f32 pairs (bit-identical)
# speedup vs baseline: 1.0007x; 1.0007x over previous
; __device__ void attn_item(const Params& p, char* lds, int bh, int qi) {
;     ...
;     S0 = __builtin_amdgcn_mfma_f32_32x32x16_bf16(*(const bf16x8*)(ks_), qf[0], cb, 0, 0, 0);
; #pragma unroll
;     for (int ks = 1; ks < 4; ++ks) S0 = __builtin_amdgcn_mfma_f32_32x32x16_bf16(*(const bf16x8*)(ks_ + ks * 16), qf[ks], S0, 0, 0, 0);
;     S1 = __builtin_amdgcn_mfma_f32_32x32x16_bf16(*(const bf16x8*)(ks_ + 32 * LD), qf[0], cb, 0, 0, 0);
; #pragma unroll
;     for (int ks = 1; ks < 4; ++ks) S1 = __builtin_amdgcn_mfma_f32_32x32x16_bf16(*(const bf16x8*)(ks_ + 32 * LD + ks * 16), qf[ks], S1, 0, 0, 0);
;     ...
;     float mx0 = -INFINITY, mx1 = -INFINITY, ps0 = 0.f, ps1 = 0.f;
; #pragma unroll
;     for (int r = 0; r < 16; r += 2) mx0 = fmaxf(fmaxf(mx0, S0[r]), S0[r + 1]);
; #pragma unroll
;     for (int r = 0; r < 16; ++r) { S0[r] = __builtin_amdgcn_exp2f(S0[r]); ps0 += S0[r]; }
; #pragma unroll
;     for (int sp = 0; sp < 2; ++sp) {
;       u32x4 pw;
;       pw.x = pk2(S0[8 * sp + 0], S0[8 * sp + 1]); pw.y = pk2(S0[8 * sp + 2], S0[8 * sp + 3]);
;       pw.z = pk2(S0[8 * sp + 4], S0[8 * sp + 5]); pw.w = pk2(S0[8 * sp + 6], S0[8 * sp + 7]);
;       const bf16x8 pb = __builtin_bit_cast(bf16x8, pw);
; #pragma unroll
;       for (int d = 0; d < 2; ++d) O[d] = __builtin_amdgcn_mfma_f32_32x32x16_bf16(*(const bf16x8*)(vs_ + d * 32 * LD + sp * 16), pb, O[d], 0, 0, 0);
;     }
; #pragma unroll
;     for (int r = 0; r < 16; r += 2) mx1 = fmaxf(fmaxf(mx1, S1[r]), S1[r + 1]);
; #pragma unroll
;     for (int r = 0; r < 16; ++r) { S1[r] = __builtin_amdgcn_exp2f(S1[r]); ps1 += S1[r]; }
; #pragma unroll
;     for (int sp = 0; sp < 2; ++sp) {
;       u32x4 pw;
;       pw.x = pk2(S1[8 * sp + 0], S1[8 * sp + 1]); pw.y = pk2(S1[8 * sp + 2], S1[8 * sp + 3]);
;       pw.z = pk2(S1[8 * sp + 4], S1[8 * sp + 5]); pw.w = pk2(S1[8 * sp + 6], S1[8 * sp + 7]);
;       const bf16x8 pb = __builtin_bit_cast(bf16x8, pw);
; #pragma unroll
;       for (int d = 0; d < 2; ++d) O[d] = __builtin_amdgcn_mfma_f32_32x32x16_bf16(*(const bf16x8*)(vs_ + d * 32 * LD + 32 + sp * 16), pb, O[d], 0, 0, 0);
;     }
;     lsum += ps0 + ps1;
;     ...
;     __builtin_amdgcn_sched_group_barrier(0x008, 4, 0);
; #pragma unroll
;     for (int i = 0; i < 4; ++i) { __builtin_amdgcn_sched_group_barrier(0x008, 1, 0); __builtin_amdgcn_sched_group_barrier(0x002, 12, 0); }
; #pragma unroll
.LBB0_436:
	s_and_b32 s26, s6, 64
	s_mulk_i32 s26, 0x90
	v_add_u32_e32 v127, s26, v119
	ds_read_b128 v[90:93], v127 offset:4672
	s_add_i32 s26, s6, 63
	v_cmp_le_u32_e32 vcc, s26, v112
	s_xor_b64 s[22:23], s[22:23], -1
	s_or_b64 s[22:23], s[22:23], vcc
	s_and_saveexec_b64 s[26:27], s[22:23]
	s_xor_b64 s[22:23], exec, s[26:27]
	s_cbranch_execz .LBB0_440
	ds_read_b128 v[128:131], v127
	ds_read_b128 v[132:135], v127 offset:32
	v_cndmask_b32_e64 v50, v125, -v107, s[24:25]
	v_mov_b32_e32 v51, v50
	v_mov_b32_e32 v52, v50
	v_mov_b32_e32 v53, v50
	v_mov_b32_e32 v54, v50
	v_mov_b32_e32 v55, v50
	v_mov_b32_e32 v56, v50
	v_mov_b32_e32 v57, v50
	v_mov_b32_e32 v58, v50
	v_mov_b32_e32 v59, v50
	v_mov_b32_e32 v60, v50
	v_mov_b32_e32 v61, v50
	v_mov_b32_e32 v62, v50
	v_mov_b32_e32 v63, v50
	v_mov_b32_e32 v64, v50
	v_mov_b32_e32 v65, v50
	v_cmp_lt_i32_e32 vcc, v156, v157
	s_waitcnt lgkmcnt(1)
	v_mfma_f32_32x32x16_bf16 v[34:49], v[128:131], v[66:69], v[50:65]
	ds_read_b128 v[128:131], v127 offset:4608
	ds_read_b128 v[136:139], v127 offset:4640
	s_waitcnt lgkmcnt(2)
	v_mfma_f32_32x32x16_bf16 v[34:49], v[132:135], v[70:73], v[34:49]
	s_waitcnt lgkmcnt(1)
	v_mfma_f32_32x32x16_bf16 v[50:65], v[128:131], v[66:69], v[50:65]
	ds_read_b128 v[128:131], v127 offset:64
	ds_read_b128 v[132:135], v127 offset:96
	s_waitcnt lgkmcnt(1)
	v_mfma_f32_32x32x16_bf16 v[34:49], v[128:131], v[74:77], v[34:49]
	ds_read_b128 v[128:131], v127 offset:4704
	v_mfma_f32_32x32x16_bf16 v[50:65], v[136:139], v[70:73], v[50:65]
	s_waitcnt lgkmcnt(1)
	v_mfma_f32_32x32x16_bf16 v[34:49], v[132:135], v[78:81], v[34:49]
	v_mfma_f32_32x32x16_bf16 v[50:65], v[90:93], v[74:77], v[50:65]
	s_nop 10
	v_exp_f32_e32 v140, v34
	v_max_f32_e32 v34, v34, v34
	v_max_f32_e32 v34, 0xff800000, v34
	v_max3_f32 v34, v34, v35, v36
	v_max3_f32 v34, v34, v37, v38
	v_max3_f32 v34, v34, v39, v40
	v_max3_f32 v34, v34, v41, v42
	s_waitcnt lgkmcnt(0)
	v_mfma_f32_32x32x16_bf16 v[50:65], v[128:131], v[78:81], v[50:65]
	v_exp_f32_e32 v142, v35
	v_exp_f32_e32 v144, v36
	v_exp_f32_e32 v146, v37
	v_exp_f32_e32 v148, v38
	v_exp_f32_e32 v150, v39
	v_exp_f32_e32 v152, v40
	v_exp_f32_e32 v154, v41
	v_max3_f32 v34, v34, v43, v44
	v_exp_f32_e32 v158, v42
	v_exp_f32_e32 v160, v43
	v_exp_f32_e32 v162, v44
	v_exp_f32_e32 v164, v45
	v_max3_f32 v34, v34, v45, v46
	ds_read_b128 v[38:41], v127 offset:18432
	ds_read_b128 v[42:45], v127 offset:23040
	v_exp_f32_e32 v170, v48
	v_max3_f32 v48, v34, v47, v48
	v_cvt_pk_bf16_f32 v34, v140, v142
	v_cvt_pk_bf16_f32 v35, v144, v146
	v_cvt_pk_bf16_f32 v36, v148, v150
	v_cvt_pk_bf16_f32 v37, v152, v154
	v_exp_f32_e32 v166, v46
	v_max3_f32 v46, v50, s34, v51
	s_waitcnt lgkmcnt(1)
	v_mfma_f32_32x32x16_bf16 v[18:33], v[38:41], v[34:37], v[18:33]
	v_max3_f32 v46, v46, v52, v53
	v_exp_f32_e32 v141, v50
	v_max3_f32 v38, v46, v54, v55
	v_exp_f32_e32 v143, v51
	v_exp_f32_e32 v168, v47
	v_exp_f32_e32 v172, v49
	v_max3_f32 v38, v38, v56, v57
	s_waitcnt lgkmcnt(0)
	v_mfma_f32_32x32x16_bf16 v[2:17], v[42:45], v[34:37], v[2:17]
	v_exp_f32_e32 v145, v52
	ds_read_b128 v[128:131], v127 offset:18464
	ds_read_b128 v[132:135], v127 offset:23072
	v_max3_f32 v38, v38, v58, v59
	v_exp_f32_e32 v147, v53
	v_max3_f32 v38, v38, v60, v61
	v_add_f32_e32 v34, 0, v140
	v_add_f32_e32 v35, 0, v141
	v_max3_f32 v38, v38, v62, v63
	v_add_f32_e32 v42, v142, v34
	v_add_f32_e32 v43, v143, v35
	v_cvt_pk_bf16_f32 v90, v158, v160
	v_cvt_pk_bf16_f32 v91, v162, v164
	v_cvt_pk_bf16_f32 v92, v166, v168
	v_cvt_pk_bf16_f32 v93, v170, v172
	v_max3_f32 v136, v38, v64, v65
	ds_read_b128 v[38:41], v127 offset:18528
	ds_read_b128 v[34:37], v127 offset:18496
	v_add_f32_e32 v42, v144, v42
	v_add_f32_e32 v43, v145, v43
	s_waitcnt lgkmcnt(3)
	v_mfma_f32_32x32x16_bf16 v[18:33], v[128:131], v[90:93], v[18:33]
	v_add_f32_e64 v46, v146, v42
	v_add_f32_e64 v47, v147, v43
	ds_read_b128 v[42:45], v127 offset:23104
	v_exp_f32_e32 v149, v54
	v_exp_f32_e32 v151, v55
	v_exp_f32_e32 v153, v56
	v_exp_f32_e32 v155, v57
	v_cvt_pk_bf16_f32 v50, v141, v143
	s_waitcnt lgkmcnt(3)
	v_mfma_f32_32x32x16_bf16 v[2:17], v[132:135], v[90:93], v[2:17]
	v_cvt_pk_bf16_f32 v51, v145, v147
	v_cvt_pk_bf16_f32 v52, v149, v151
	v_cvt_pk_bf16_f32 v53, v153, v155
	v_exp_f32_e32 v159, v58
	v_exp_f32_e32 v161, v59
	v_exp_f32_e32 v163, v60
	v_exp_f32_e32 v165, v61
	s_waitcnt lgkmcnt(1)
	v_mfma_f32_32x32x16_bf16 v[18:33], v[34:37], v[50:53], v[18:33]
	v_exp_f32_e32 v167, v62
	v_exp_f32_e32 v169, v63
	v_exp_f32_e32 v171, v64
	v_exp_f32_e32 v173, v65
	v_add_f32_e32 v46, v148, v46
	v_add_f32_e32 v47, v149, v47
	v_cvt_pk_bf16_f32 v34, v159, v161
	v_add_f32_e32 v46, v150, v46
	v_add_f32_e32 v47, v151, v47
	s_waitcnt lgkmcnt(0)
	v_mfma_f32_32x32x16_bf16 v[2:17], v[42:45], v[50:53], v[2:17]
	ds_read_b128 v[42:45], v127 offset:23136
	v_add_f32_e64 v46, v152, v46
	v_add_f32_e64 v47, v153, v47
	v_cvt_pk_bf16_f32 v35, v163, v165
	v_cvt_pk_bf16_f32 v36, v167, v169
	v_cvt_pk_bf16_f32 v37, v171, v173
	v_add_f32_e32 v46, v154, v46
	v_add_f32_e32 v47, v155, v47
	s_nop 0
	v_mfma_f32_32x32x16_bf16 v[18:33], v[38:41], v[34:37], v[18:33]
	v_add_f32_e64 v38, v158, v46
	v_add_f32_e64 v39, v159, v47
	v_max3_f32 v40, v48, v49, v136
	v_add_f32_e64 v38, v160, v38
	v_add_f32_e64 v39, v161, v39
	v_add_f32_e32 v38, v162, v38
	v_add_f32_e32 v39, v163, v39
	s_nop 0
	v_add_f32_e32 v38, v164, v38
	v_add_f32_e32 v39, v165, v39
	s_waitcnt lgkmcnt(0)
	v_mfma_f32_32x32x16_bf16 v[2:17], v[42:45], v[34:37], v[2:17]
	v_cndmask_b32_e32 v34, v1, v156, vcc
	v_lshlrev_b32_e32 v34, 2, v34
	v_add_f32_e64 v38, v166, v38
	v_add_f32_e64 v39, v167, v39
	ds_bpermute_b32 v36, v34, v40
	v_add_f32_e32 v38, v168, v38
	v_add_f32_e32 v39, v169, v39
	s_nop 0
	v_add_f32_e32 v34, v170, v38
	v_add_f32_e32 v35, v171, v39
	s_nop 0
	v_add_f32_e32 v34, v172, v34
	v_add_f32_e32 v35, v173, v35
	s_nop 0
	v_add_f32_e32 v34, v34, v35
	v_add_f32_e32 v126, v126, v34
	s_waitcnt lgkmcnt(0)
	v_max_f32_e32 v34, v36, v36
	v_max_f32_e32 v34, v40, v34
	v_cmp_lt_f32_e32 vcc, s35, v34
	s_cbranch_vccz .LBB0_439
	s_nop 0
	v_cndmask_b32_e32 v35, 0, v34, vcc
	v_exp_f32_e64 v34, -v35
	v_add_f32_e32 v107, v107, v35
	v_mul_f32_e32 v126, v126, v34
	v_pk_mul_f32 v[32:33], v[32:33], v[34:35] op_sel_hi:[1,0]
	v_pk_mul_f32 v[30:31], v[30:31], v[34:35] op_sel_hi:[1,0]
	v_pk_mul_f32 v[28:29], v[28:29], v[34:35] op_sel_hi:[1,0]
	v_pk_mul_f32 v[26:27], v[26:27], v[34:35] op_sel_hi:[1,0]
	v_pk_mul_f32 v[24:25], v[24:25], v[34:35] op_sel_hi:[1,0]
	v_pk_mul_f32 v[22:23], v[22:23], v[34:35] op_sel_hi:[1,0]
	v_pk_mul_f32 v[20:21], v[20:21], v[34:35] op_sel_hi:[1,0]
	v_pk_mul_f32 v[18:19], v[18:19], v[34:35] op_sel_hi:[1,0]
	v_pk_mul_f32 v[16:17], v[16:17], v[34:35] op_sel_hi:[1,0]
	v_pk_mul_f32 v[14:15], v[14:15], v[34:35] op_sel_hi:[1,0]
	v_pk_mul_f32 v[12:13], v[12:13], v[34:35] op_sel_hi:[1,0]
	v_pk_mul_f32 v[10:11], v[10:11], v[34:35] op_sel_hi:[1,0]
	v_pk_mul_f32 v[8:9], v[8:9], v[34:35] op_sel_hi:[1,0]
	v_pk_mul_f32 v[6:7], v[6:7], v[34:35] op_sel_hi:[1,0]
	v_pk_mul_f32 v[4:5], v[4:5], v[34:35] op_sel_hi:[1,0]
	v_pk_mul_f32 v[2:3], v[2:3], v[34:35] op_sel_hi:[1,0]
; __device__ __forceinline__ int rm32(int reg, int h) { return (reg & 3) + 8 * (reg >> 2) + 4 * h; }
; __device__ void attn_item(const Params& p, char* lds, int bh, int qi) {
;     ...
;     f32x16 cb, S0, S1;
;     {
;       const float cinit = sel ? -mref : -INFINITY;
; #pragma unroll
;       for (int r = 0; r < 16; ++r) cb[r] = cinit;
;     }
;     S0 = __builtin_amdgcn_mfma_f32_32x32x16_bf16(*(const bf16x8*)(ks_), qf[0], cb, 0, 0, 0);
; #pragma unroll
;     for (int ks = 1; ks < 4; ++ks) S0 = __builtin_amdgcn_mfma_f32_32x32x16_bf16(*(const bf16x8*)(ks_ + ks * 16), qf[ks], S0, 0, 0, 0);
;     S1 = __builtin_amdgcn_mfma_f32_32x32x16_bf16(*(const bf16x8*)(ks_ + 32 * LD), qf[0], cb, 0, 0, 0);
; #pragma unroll
;     for (int ks = 1; ks < 4; ++ks) S1 = __builtin_amdgcn_mfma_f32_32x32x16_bf16(*(const bf16x8*)(ks_ + 32 * LD + ks * 16), qf[ks], S1, 0, 0, 0);
;     if constexpr (DIAG) {
;       const int qrel = wave * 32 + l31;
; #pragma unroll
;       for (int r = 0; r < 16; ++r) {
;         const int krel = sub * 64 + rm32(r, h);
;         S0[r] = (krel <= qrel) ? S0[r] : -INFINITY;
;         S1[r] = (krel + 32 <= qrel) ? S1[r] : -INFINITY;
;       }
;     }
;     float mx0 = -INFINITY, mx1 = -INFINITY, ps0 = 0.f, ps1 = 0.f;
; #pragma unroll
;     for (int r = 0; r < 16; r += 2) mx0 = fmaxf(fmaxf(mx0, S0[r]), S0[r + 1]);
; #pragma unroll
;     for (int r = 0; r < 16; ++r) { S0[r] = __builtin_amdgcn_exp2f(S0[r]); ps0 += S0[r]; }
.LBB0_439:
.LBB0_440:
	s_andn2_saveexec_b64 s[22:23], s[22:23]
	s_cbranch_execz .LBB0_443
	ds_read_b128 v[128:131], v127
	ds_read_b128 v[132:135], v127 offset:32
	v_xor_b32_e32 v34, 0x80000000, v107
	v_mov_b32_e32 v35, v34
	v_mov_b32_e32 v36, v34
	v_mov_b32_e32 v37, v34
	v_mov_b32_e32 v38, v34
	v_mov_b32_e32 v39, v34
	v_mov_b32_e32 v40, v34
	v_mov_b32_e32 v41, v34
	v_mov_b32_e32 v42, v34
	v_mov_b32_e32 v43, v34
	v_mov_b32_e32 v44, v34
	v_mov_b32_e32 v45, v34
	v_mov_b32_e32 v46, v34
	v_mov_b32_e32 v47, v34
	v_mov_b32_e32 v48, v34
	v_mov_b32_e32 v49, v34
	s_waitcnt lgkmcnt(1)
	s_nop 0
	v_mfma_f32_32x32x16_bf16 v[50:65], v[128:131], v[66:69], v[34:49]
	ds_read_b128 v[128:131], v127 offset:4608
	ds_read_b128 v[136:139], v127 offset:4640
	s_waitcnt lgkmcnt(1)
	v_mfma_f32_32x32x16_bf16 v[34:49], v[128:131], v[66:69], v[34:49]
	s_waitcnt lgkmcnt(0)
	v_mfma_f32_32x32x16_bf16 v[34:49], v[136:139], v[70:73], v[34:49]
	v_mfma_f32_32x32x16_bf16 v[50:65], v[132:135], v[70:73], v[50:65]
	v_add_u32_e32 v132, s6, v120
	v_cmp_le_u32_e32 vcc, v132, v113
	v_add_u32_e32 v133, 32, v132
	v_mfma_f32_32x32x16_bf16 v[34:49], v[90:93], v[74:77], v[34:49]
	ds_read_b128 v[90:93], v127 offset:64
	ds_read_b128 v[128:131], v127 offset:96
	s_waitcnt lgkmcnt(1)
	v_mfma_f32_32x32x16_bf16 v[50:65], v[90:93], v[74:77], v[50:65]
	ds_read_b128 v[90:93], v127 offset:4704
	s_waitcnt lgkmcnt(1)
	v_mfma_f32_32x32x16_bf16 v[50:65], v[128:131], v[78:81], v[50:65]
	ds_read_b128 v[128:131], v127 offset:18432
	s_waitcnt lgkmcnt(1)
	v_mfma_f32_32x32x16_bf16 v[34:49], v[90:93], v[78:81], v[34:49]
	s_nop 8
	v_cndmask_b32_e32 v50, v125, v50, vcc
	v_cmp_le_u32_e32 vcc, v133, v113
	s_nop 1
	v_cndmask_b32_e32 v90, v125, v34, vcc
	v_cmp_lt_u32_e32 vcc, v132, v113
	s_nop 1
	v_cndmask_b32_e32 v34, v125, v51, vcc
	v_add_u32_e32 v51, 33, v132
	v_cmp_le_u32_e32 vcc, v51, v113
	v_add_u32_e32 v51, 34, v132
	s_nop 0
	v_cndmask_b32_e32 v92, v125, v35, vcc
	v_add_u32_e32 v35, 2, v132
	v_cmp_le_u32_e32 vcc, v35, v113
	s_nop 1
	v_cndmask_b32_e32 v35, v125, v52, vcc
	v_cmp_le_u32_e32 vcc, v51, v113
	s_nop 1
	v_cndmask_b32_e32 v134, v125, v36, vcc
	v_add_u32_e32 v36, 3, v132
	v_cmp_le_u32_e32 vcc, v36, v113
	v_add_u32_e32 v36, 35, v132
	s_nop 0
	v_cndmask_b32_e32 v136, v125, v53, vcc
	v_cmp_le_u32_e32 vcc, v36, v113
	v_add_u32_e32 v36, 8, v132
	s_nop 0
	v_cndmask_b32_e32 v138, v125, v37, vcc
	v_cmp_le_u32_e32 vcc, v36, v113
	v_add_u32_e32 v36, 40, v132
	s_nop 0
	v_cndmask_b32_e32 v54, v125, v54, vcc
	v_cmp_le_u32_e32 vcc, v36, v113
	v_add_u32_e32 v36, 9, v132
	s_nop 0
	v_cndmask_b32_e32 v140, v125, v38, vcc
	v_cmp_le_u32_e32 vcc, v36, v113
	v_add_u32_e32 v36, 41, v132
	s_nop 0
	v_cndmask_b32_e32 v142, v125, v55, vcc
	v_cmp_le_u32_e32 vcc, v36, v113
	v_add_u32_e32 v36, 10, v132
	v_exp_f32_e32 v55, v50
	v_cndmask_b32_e32 v144, v125, v39, vcc
	v_cmp_le_u32_e32 vcc, v36, v113
	v_add_u32_e32 v36, 42, v132
	s_nop 0
	v_cndmask_b32_e32 v56, v125, v56, vcc
	v_cmp_le_u32_e32 vcc, v36, v113
	v_add_u32_e32 v36, 11, v132
	v_exp_f32_e32 v91, v56
	v_cndmask_b32_e32 v145, v125, v40, vcc
	v_cmp_le_u32_e32 vcc, v36, v113
	v_add_u32_e32 v36, 43, v132
	s_nop 0
	v_cndmask_b32_e32 v146, v125, v57, vcc
	v_cmp_le_u32_e32 vcc, v36, v113
	v_add_u32_e32 v36, 16, v132
	v_exp_f32_e32 v57, v34
	v_cndmask_b32_e32 v147, v125, v41, vcc
	v_cmp_le_u32_e32 vcc, v36, v113
	v_add_u32_e32 v36, 48, v132
	ds_read_b128 v[38:41], v127 offset:23040
	v_cndmask_b32_e32 v58, v125, v58, vcc
	v_cmp_le_u32_e32 vcc, v36, v113
	v_add_u32_e32 v36, 17, v132
	v_exp_f32_e32 v93, v146
	v_cndmask_b32_e32 v148, v125, v42, vcc
	v_cmp_le_u32_e32 vcc, v36, v113
	v_add_u32_e32 v36, 49, v132
	v_cvt_pk_bf16_f32 v37, v91, v93
	v_cndmask_b32_e32 v149, v125, v59, vcc
	v_cmp_le_u32_e32 vcc, v36, v113
	v_add_u32_e32 v36, 18, v132
	v_exp_f32_e32 v59, v35
	v_cndmask_b32_e32 v150, v125, v43, vcc
	v_cmp_le_u32_e32 vcc, v36, v113
	v_add_u32_e32 v36, 50, v132
	v_exp_f32_e32 v133, v58
	v_cndmask_b32_e32 v60, v125, v60, vcc
	v_cmp_le_u32_e32 vcc, v36, v113
	v_add_u32_e32 v36, 19, v132
	v_exp_f32_e32 v135, v149
	v_cndmask_b32_e32 v151, v125, v44, vcc
	v_cmp_le_u32_e32 vcc, v36, v113
	v_add_u32_e32 v36, 51, v132
	s_nop 0
	v_cndmask_b32_e32 v152, v125, v61, vcc
	v_cmp_le_u32_e32 vcc, v36, v113
	v_add_u32_e32 v36, 24, v132
	v_exp_f32_e32 v61, v136
	v_cndmask_b32_e32 v153, v125, v45, vcc
	v_cmp_le_u32_e32 vcc, v36, v113
	v_add_u32_e32 v36, 56, v132
	s_nop 0
	v_cndmask_b32_e32 v62, v125, v62, vcc
	v_cmp_le_u32_e32 vcc, v36, v113
	v_add_u32_e32 v36, 25, v132
	v_exp_f32_e32 v137, v62
	v_cndmask_b32_e32 v154, v125, v46, vcc
	v_cmp_le_u32_e32 vcc, v36, v113
	v_add_u32_e32 v36, 57, v132
	s_nop 0
	v_cndmask_b32_e32 v155, v125, v63, vcc
	v_cmp_le_u32_e32 vcc, v36, v113
	v_add_u32_e32 v36, 26, v132
	v_exp_f32_e32 v63, v54
	v_cndmask_b32_e32 v158, v125, v47, vcc
	v_cmp_le_u32_e32 vcc, v36, v113
	v_add_u32_e32 v36, 58, v132
	v_exp_f32_e32 v139, v155
	v_cndmask_b32_e32 v64, v125, v64, vcc
	v_cmp_le_u32_e32 vcc, v36, v113
	v_add_u32_e32 v36, 27, v132
	v_exp_f32_e32 v141, v64
	v_cndmask_b32_e32 v159, v125, v48, vcc
	v_cmp_le_u32_e32 vcc, v36, v113
	v_add_u32_e32 v36, 59, v132
	s_nop 0
	v_cndmask_b32_e32 v160, v125, v65, vcc
	v_exp_f32_e32 v65, v142
	v_cmp_le_u32_e32 vcc, v36, v113
	v_max_f32_e32 v36, v50, v50
	v_max_f32_e32 v36, 0xff800000, v36
	v_max3_f32 v132, v36, v34, v35
	v_cvt_pk_bf16_f32 v34, v55, v57
	v_cvt_pk_bf16_f32 v35, v59, v61
	v_cvt_pk_bf16_f32 v36, v63, v65
	v_exp_f32_e32 v143, v160
	v_cndmask_b32_e32 v161, v125, v49, vcc
	s_waitcnt lgkmcnt(1)
; __device__ __forceinline__ unsigned pk2(float lo, float hi) { f32x2_t v = {lo, hi}; bf16x2_t b = __builtin_convertvector(v, bf16x2_t); return __builtin_bit_cast(unsigned, b); }
; __device__ void attn_item(const Params& p, char* lds, int bh, int qi) {
;     ...
;     for (int sp = 0; sp < 2; ++sp) {
;       u32x4 pw;
;       pw.x = pk2(S0[8 * sp + 0], S0[8 * sp + 1]); pw.y = pk2(S0[8 * sp + 2], S0[8 * sp + 3]);
;       pw.z = pk2(S0[8 * sp + 4], S0[8 * sp + 5]); pw.w = pk2(S0[8 * sp + 6], S0[8 * sp + 7]);
;       const bf16x8 pb = __builtin_bit_cast(bf16x8, pw);
; #pragma unroll
;       for (int d = 0; d < 2; ++d) O[d] = __builtin_amdgcn_mfma_f32_32x32x16_bf16(*(const bf16x8*)(vs_ + d * 32 * LD + sp * 16), pb, O[d], 0, 0, 0);
;     }
; #pragma unroll
;     for (int r = 0; r < 16; r += 2) mx1 = fmaxf(fmaxf(mx1, S1[r]), S1[r + 1]);
; #pragma unroll
;     for (int r = 0; r < 16; ++r) { S1[r] = __builtin_amdgcn_exp2f(S1[r]); ps1 += S1[r]; }
; #pragma unroll
;     for (int sp = 0; sp < 2; ++sp) {
;       u32x4 pw;
;       pw.x = pk2(S1[8 * sp + 0], S1[8 * sp + 1]); pw.y = pk2(S1[8 * sp + 2], S1[8 * sp + 3]);
;       pw.z = pk2(S1[8 * sp + 4], S1[8 * sp + 5]); pw.w = pk2(S1[8 * sp + 6], S1[8 * sp + 7]);
;       const bf16x8 pb = __builtin_bit_cast(bf16x8, pw);
; #pragma unroll
;       for (int d = 0; d < 2; ++d) O[d] = __builtin_amdgcn_mfma_f32_32x32x16_bf16(*(const bf16x8*)(vs_ + d * 32 * LD + 32 + sp * 16), pb, O[d], 0, 0, 0);
;     }
;     lsum += ps0 + ps1;
;     ...
;     __builtin_amdgcn_sched_group_barrier(0x008, 4, 0);
; #pragma unroll
;     for (int i = 0; i < 4; ++i) { __builtin_amdgcn_sched_group_barrier(0x008, 1, 0); __builtin_amdgcn_sched_group_barrier(0x002, 12, 0); }
; #pragma unroll
;     for (int i = 0; i < 4; ++i) { __builtin_amdgcn_sched_group_barrier(0x008, 1, 0); __builtin_amdgcn_sched_group_barrier(0x002, 12, 0); }
;     __builtin_amdgcn_sched_group_barrier(0x008, 4, 0);
;     ...
;     float mx = fmaxf(mx0, mx1);
;     mx = fmaxf(mx, __shfl_xor(mx, 32));
;     if (__ballot(mx > 8.f) != 0ull) {
;       const float delta = (mx > 8.f) ? mx : 0.f;
;       const float alpha = __builtin_amdgcn_exp2f(-delta);
;       mref += delta;
;       lsum *= alpha;
; #pragma unroll
;       for (int d = 0; d < 2; ++d)
; #pragma unroll
;         for (int r = 0; r < 16; ++r) O[d][r] *= alpha;
;     }
	v_mfma_f32_32x32x16_bf16 v[18:33], v[128:131], v[34:37], v[18:33]
	v_exp_f32_e32 v129, v60
	v_exp_f32_e32 v131, v152
	ds_read_b128 v[42:45], v127 offset:18464
	ds_read_b128 v[46:49], v127 offset:18528
	v_exp_f32_e32 v128, v151
	v_exp_f32_e32 v130, v153
	v_cmp_lt_i32_e32 vcc, v156, v157
	s_waitcnt lgkmcnt(2)
	v_mfma_f32_32x32x16_bf16 v[2:17], v[38:41], v[34:37], v[2:17]
	ds_read_b128 v[38:41], v127 offset:23072
	ds_read_b128 v[50:53], v127 offset:18496
	v_cvt_pk_bf16_f32 v34, v133, v135
	v_cvt_pk_bf16_f32 v35, v129, v131
	v_cvt_pk_bf16_f32 v36, v137, v139
	v_cvt_pk_bf16_f32 v37, v141, v143
	s_waitcnt lgkmcnt(3)
	s_nop 0
	v_mfma_f32_32x32x16_bf16 v[18:33], v[42:45], v[34:37], v[18:33]
	v_max3_f32 v42, v132, v136, v54
	v_exp_f32_e32 v54, v90
	v_max3_f32 v42, v42, v142, v56
	v_exp_f32_e32 v56, v92
	v_max3_f32 v42, v42, v146, v58
	v_exp_f32_e32 v58, v134
	v_max3_f32 v42, v42, v149, v60
	s_waitcnt lgkmcnt(1)
	v_mfma_f32_32x32x16_bf16 v[2:17], v[38:41], v[34:37], v[2:17]
	v_max3_f32 v34, v90, s34, v92
	v_max3_f32 v34, v34, v134, v138
	v_max3_f32 v34, v34, v140, v144
	v_max3_f32 v34, v34, v145, v147
	v_max3_f32 v34, v34, v148, v150
	v_max3_f32 v34, v34, v151, v153
	v_exp_f32_e32 v60, v138
	v_max3_f32 v42, v42, v152, v62
	v_max3_f32 v149, v34, v154, v158
	v_add_f32_e32 v34, 0, v54
	v_add_f32_e32 v35, 0, v55
	v_exp_f32_e32 v62, v140
	v_max3_f32 v146, v42, v155, v64
	v_add_f32_e32 v34, v56, v34
	v_add_f32_e32 v35, v57, v35
	v_exp_f32_e32 v64, v144
	v_add_f32_e32 v34, v58, v34
	v_add_f32_e32 v35, v59, v35
	v_exp_f32_e32 v90, v145
	v_add_f32_e32 v34, v60, v34
	v_add_f32_e32 v35, v61, v35
	v_exp_f32_e32 v92, v147
	ds_read_b128 v[42:45], v127 offset:23104
	v_exp_f32_e32 v132, v148
	v_add_f32_e32 v34, v62, v34
	v_add_f32_e32 v35, v63, v35
	v_exp_f32_e32 v134, v150
	v_add_f32_e32 v38, v64, v34
	v_add_f32_e32 v39, v65, v35
	v_exp_f32_e32 v136, v154
	v_add_f32_e32 v38, v90, v38
	v_add_f32_e32 v39, v91, v39
	v_exp_f32_e32 v138, v158
	v_add_f32_e32 v38, v92, v38
	v_add_f32_e32 v39, v93, v39
	v_cvt_pk_bf16_f32 v34, v54, v56
	v_add_f32_e32 v38, v132, v38
	v_add_f32_e32 v39, v133, v39
	v_cvt_pk_bf16_f32 v35, v58, v60
	v_add_f32_e32 v38, v134, v38
	v_add_f32_e32 v39, v135, v39
	v_cvt_pk_bf16_f32 v36, v62, v64
	v_add_f32_e32 v38, v128, v38
	v_add_f32_e32 v39, v129, v39
	v_cvt_pk_bf16_f32 v37, v90, v92
	v_add_f32_e32 v38, v130, v38
	v_add_f32_e32 v39, v131, v39
	v_exp_f32_e32 v140, v159
	v_add_f32_e32 v38, v136, v38
	v_add_f32_e32 v39, v137, v39
	s_waitcnt lgkmcnt(1)
	v_mfma_f32_32x32x16_bf16 v[18:33], v[50:53], v[34:37], v[18:33]
	v_exp_f32_e32 v142, v161
	s_waitcnt lgkmcnt(0)
	v_mfma_f32_32x32x16_bf16 v[2:17], v[42:45], v[34:37], v[2:17]
	v_add_f32_e64 v34, v138, v38
	v_add_f32_e64 v35, v139, v39
	ds_read_b128 v[38:41], v127 offset:23136
	v_max3_f32 v44, v149, v159, v161
	v_cndmask_b32_e32 v45, v1, v156, vcc
	v_add_f32_e32 v42, v140, v34
	v_add_f32_e32 v43, v141, v35
	v_cvt_pk_bf16_f32 v34, v132, v134
	v_cvt_pk_bf16_f32 v35, v128, v130
	v_cvt_pk_bf16_f32 v36, v136, v138
	v_cvt_pk_bf16_f32 v37, v140, v142
	v_max3_f32 v44, v146, v160, v44
	v_lshlrev_b32_e32 v45, 2, v45
	v_mfma_f32_32x32x16_bf16 v[18:33], v[46:49], v[34:37], v[18:33]
	ds_bpermute_b32 v45, v45, v44
	v_add_f32_e64 v42, v142, v42
	v_add_f32_e64 v43, v143, v43
	s_waitcnt lgkmcnt(1)
	v_mfma_f32_32x32x16_bf16 v[2:17], v[38:41], v[34:37], v[2:17]
	v_add_f32_e32 v34, v42, v43
	v_add_f32_e32 v126, v126, v34
	s_waitcnt lgkmcnt(0)
	v_max_f32_e32 v34, v45, v45
	v_max_f32_e32 v34, v44, v34
	v_cmp_lt_f32_e32 vcc, s35, v34
	s_cbranch_vccz .LBB0_443
	s_nop 0
	v_cndmask_b32_e32 v35, 0, v34, vcc
	v_exp_f32_e64 v34, -v35
	v_add_f32_e32 v107, v107, v35
	v_mul_f32_e32 v126, v126, v34
	v_pk_mul_f32 v[32:33], v[32:33], v[34:35] op_sel_hi:[1,0]
	v_pk_mul_f32 v[30:31], v[30:31], v[34:35] op_sel_hi:[1,0]
	v_pk_mul_f32 v[28:29], v[28:29], v[34:35] op_sel_hi:[1,0]
	v_pk_mul_f32 v[26:27], v[26:27], v[34:35] op_sel_hi:[1,0]
	v_pk_mul_f32 v[24:25], v[24:25], v[34:35] op_sel_hi:[1,0]
	v_pk_mul_f32 v[22:23], v[22:23], v[34:35] op_sel_hi:[1,0]
	v_pk_mul_f32 v[20:21], v[20:21], v[34:35] op_sel_hi:[1,0]
	v_pk_mul_f32 v[18:19], v[18:19], v[34:35] op_sel_hi:[1,0]
	v_pk_mul_f32 v[16:17], v[16:17], v[34:35] op_sel_hi:[1,0]
	v_pk_mul_f32 v[14:15], v[14:15], v[34:35] op_sel_hi:[1,0]
	v_pk_mul_f32 v[12:13], v[12:13], v[34:35] op_sel_hi:[1,0]
	v_pk_mul_f32 v[10:11], v[10:11], v[34:35] op_sel_hi:[1,0]
	v_pk_mul_f32 v[8:9], v[8:9], v[34:35] op_sel_hi:[1,0]
	v_pk_mul_f32 v[6:7], v[6:7], v[34:35] op_sel_hi:[1,0]
	v_pk_mul_f32 v[4:5], v[4:5], v[34:35] op_sel_hi:[1,0]
	v_pk_mul_f32 v[2:3], v[2:3], v[34:35] op_sel_hi:[1,0]
